# rms/final-norm phases: sample-row waves hand their two prompt row-groups to waves 1,2 / 5,6 (longest per-wave chain 6 -> 4 memory rounds)
# speedup vs baseline: 1.0080x; 1.0023x over previous
.LBB0_559:
	s_or_b64 exec, exec, s[30:31]
	v_readlane_b32 s0, v251, 19
	s_cmpk_lt_i32 s0, 0x1000
	s_cselect_b64 s[2:3], -1, 0
	v_mov_b32_e32 v64, v184
	v_writelane_b32 v251, s2, 31
	s_waitcnt lgkmcnt(0)
	s_barrier
	v_writelane_b32 v251, s3, 32
	s_cmpk_gt_i32 s0, 0xfff
	v_ashrrev_i32_e32 v65, 31, v64
	s_cbranch_scc1 .LBB0_562
	v_readlane_b32 s98, v251, 19
	s_and_b32 s98, s98, 3
	s_cmp_eq_u32 s98, 3
	s_cbranch_scc1 .LBB0_562
	s_movk_i32 s100, 0x2000
	s_movk_i32 s101, 0x4000
	s_cmp_eq_u32 s98, 1
	s_cselect_b32 s100, 8, s100
	s_cselect_b32 s101, 0x1ff8, s101
	s_cmp_eq_u32 s98, 2
	s_cselect_b32 s101, 4, s101
	s_cmp_eq_u32 s98, 0
	s_cselect_b32 s98, 2, 3
	s_mov_b32 s99, 0
	v_mbcnt_hi_u32_b32 v0, -1, v250
	v_and_b32_e32 v1, 64, v0
	v_add_u32_e32 v1, 64, v1
	v_xor_b32_e32 v2, 1, v0
	v_cmp_lt_i32_e32 vcc, v2, v1
	s_ashr_i32 s71, s70, 31
	s_lshl_b32 s0, s58, 5
	v_cndmask_b32_e32 v2, v0, v2, vcc
	v_lshlrev_b32_e32 v72, 2, v2
	v_xor_b32_e32 v2, 2, v0
	v_cmp_lt_i32_e32 vcc, v2, v1
	s_lshl_b64 s[2:3], s[70:71], 11
	s_add_u32 s2, s50, s2
	v_cndmask_b32_e32 v2, v0, v2, vcc
	v_lshlrev_b32_e32 v73, 2, v2
	v_xor_b32_e32 v2, 4, v0
	v_cmp_lt_i32_e32 vcc, v2, v1
	v_readlane_b32 s4, v252, 16
	s_addc_u32 s3, s51, s3
	v_cndmask_b32_e32 v2, v0, v2, vcc
	v_lshlrev_b32_e32 v74, 2, v2
	v_xor_b32_e32 v2, 8, v0
	v_cmp_lt_i32_e32 vcc, v2, v1
	v_readlane_b32 s5, v252, 17
	s_ashr_i32 s1, s0, 31
	v_cndmask_b32_e32 v2, v0, v2, vcc
	v_lshlrev_b32_e32 v75, 2, v2
	v_xor_b32_e32 v2, 16, v0
	v_cmp_lt_i32_e32 vcc, v2, v1
	s_lshl_b64 s[4:5], s[70:71], 12
	v_readlane_b32 s6, v252, 18
	v_cndmask_b32_e32 v2, v0, v2, vcc
	v_lshlrev_b32_e32 v76, 2, v2
	v_xor_b32_e32 v2, 32, v0
	v_cmp_lt_i32_e32 vcc, v2, v1
	v_readlane_b32 s7, v252, 19
	v_readlane_b32 s8, v252, 20
	v_cndmask_b32_e32 v0, v0, v2, vcc
	v_lshl_add_u64 v[2:3], v[64:65], 3, s[2:3]
	s_mov_b64 s[2:3], 0x30d4000
	v_lshl_add_u64 v[68:69], v[2:3], 0, s[2:3]
	s_lshl_b64 s[2:3], s[0:1], 11
	s_add_u32 s4, s48, s4
	v_lshlrev_b32_e32 v77, 2, v0
	v_lshlrev_b64 v[0:1], 4, v[64:65]
	v_readlane_b32 s9, v252, 21
	s_addc_u32 s5, s49, s5
	v_lshl_add_u64 v[70:71], s[4:5], 0, v[0:1]
	v_lshl_add_u64 v[66:67], s[8:9], 0, v[0:1]
	s_lshl_b64 s[4:5], s[0:1], 12
	v_mov_b32_e32 v78, 0x358637bd
	s_mov_b32 s1, 0x800000
	s_mov_b32 s6, s70
	s_movk_i32 s7, 0x1000
	v_readlane_b32 s10, v252, 22
	v_readlane_b32 s11, v252, 23
	v_readlane_b32 s12, v252, 24
	v_readlane_b32 s13, v252, 25
	v_readlane_b32 s14, v252, 26
	v_readlane_b32 s15, v252, 27
	v_readlane_b32 s16, v252, 28
	v_readlane_b32 s17, v252, 29
	v_readlane_b32 s18, v252, 30
	v_readlane_b32 s19, v252, 31
.LBB0_561:
	global_load_dwordx4 v[80:83], v[70:71], off
	global_load_dwordx4 v[84:87], v[70:71], off offset:1024
	global_load_dwordx4 v[88:91], v[70:71], off offset:2048
	global_load_dwordx4 v[92:95], v[70:71], off offset:3072
	v_add_co_u32_e32 v0, vcc, 0x1000, v70
	s_add_i32 s99, s99, 1
	s_cmp_eq_u32 s99, 2
	s_cselect_b32 s0, s101, s100
	s_cmp_ge_u32 s99, s98
	s_cselect_b32 s0, 0x4000, s0
	s_lshl_b32 s4, s0, 12
	s_mov_b32 s5, 0
	s_lshl_b32 s2, s0, 11
	s_mov_b32 s3, 0
	s_add_i32 s6, s6, s0
	s_nop 0
	v_addc_co_u32_e32 v1, vcc, 0, v71, vcc
	global_load_dwordx4 v[60:63], v[0:1], off
	global_load_dwordx4 v[56:59], v[0:1], off offset:1024
	global_load_dwordx4 v[52:55], v[0:1], off offset:2048
	global_load_dwordx4 v[48:51], v[0:1], off offset:3072
	v_add_co_u32_e32 v0, vcc, 0x2000, v70
	s_cmpk_gt_i32 s6, 0x3fff
	s_nop 0
	v_addc_co_u32_e32 v1, vcc, 0, v71, vcc
	global_load_dwordx4 v[44:47], v[0:1], off
	global_load_dwordx4 v[32:35], v[0:1], off offset:1024
	global_load_dwordx4 v[24:27], v[0:1], off offset:2048
	global_load_dwordx4 v[16:19], v[0:1], off offset:3072
	v_add_co_u32_e32 v0, vcc, 0x3000, v70
	v_addc_co_u32_e32 v1, vcc, 0, v71, vcc
	global_load_dwordx4 v[12:15], v[0:1], off
	global_load_dwordx4 v[8:11], v[0:1], off offset:1024
	global_load_dwordx4 v[4:7], v[0:1], off offset:2048
	s_nop 0
	global_load_dwordx4 v[0:3], v[0:1], off offset:3072
	s_nop 0
	global_load_dwordx4 v[40:43], v[66:67], off
	global_load_dwordx4 v[36:39], v[66:67], off offset:1024
	global_load_dwordx4 v[28:31], v[66:67], off offset:2048
	global_load_dwordx4 v[20:23], v[66:67], off offset:3072
	s_waitcnt vmcnt(8)
	v_pk_mul_f32 v[96:97], v[82:83], v[82:83]
	v_pk_mul_f32 v[98:99], v[80:81], v[80:81]
	v_mul_f32_e32 v79, v92, v92
	v_pk_mov_b32 v[100:101], v[98:99], v[96:97] op_sel:[1,0]
	v_mov_b32_e32 v99, v97
	v_pk_add_f32 v[96:97], v[100:101], v[98:99]
	v_pk_mul_f32 v[98:99], v[86:87], v[86:87]
	v_pk_mul_f32 v[100:101], v[84:85], v[84:85]
	v_pk_add_f32 v[96:97], v[96:97], v[96:97] op_sel:[0,1] op_sel_hi:[1,0]
	v_pk_mov_b32 v[102:103], v[100:101], v[98:99] op_sel:[1,0]
	v_mov_b32_e32 v101, v99
	v_pk_add_f32 v[98:99], v[102:103], v[100:101]
	v_mul_f32_e32 v100, v93, v93
	v_pk_add_f32 v[98:99], v[98:99], v[98:99] op_sel:[0,1] op_sel_hi:[1,0]
	v_mov_b32_e32 v97, v79
	v_mov_b32_e32 v99, v100
	v_pk_add_f32 v[96:97], v[96:97], v[98:99]
	v_mul_f32_e32 v98, v89, v89
	v_mul_f32_e32 v101, v94, v94
	v_pk_fma_f32 v[98:99], v[88:89], v[88:89], v[98:99] op_sel_hi:[1,1,0]
	v_mul_f32_e32 v100, v91, v91
	v_mul_f32_e32 v102, v95, v95
	v_mov_b32_e32 v99, v101
	v_pk_fma_f32 v[100:101], v[90:91], v[90:91], v[100:101] op_sel_hi:[1,1,0]
	v_lshl_add_u64 v[70:71], v[70:71], 0, s[4:5]
	v_mov_b32_e32 v101, v102
	v_pk_add_f32 v[98:99], v[98:99], v[100:101]
	s_nop 0
	v_pk_add_f32 v[96:97], v[96:97], v[98:99]
	s_nop 0
	v_add_f32_e32 v79, v96, v97
	ds_bpermute_b32 v96, v72, v79
	s_waitcnt lgkmcnt(0)
	v_add_f32_e32 v79, v79, v96
	ds_bpermute_b32 v96, v73, v79
	s_waitcnt lgkmcnt(0)
	v_add_f32_e32 v79, v79, v96
	ds_bpermute_b32 v96, v74, v79
	s_waitcnt lgkmcnt(0)
	v_add_f32_e32 v79, v79, v96
	ds_bpermute_b32 v96, v75, v79
	s_waitcnt lgkmcnt(0)
	v_add_f32_e32 v79, v79, v96
	ds_bpermute_b32 v96, v76, v79
	s_waitcnt lgkmcnt(0)
	v_add_f32_e32 v79, v79, v96
	ds_bpermute_b32 v96, v77, v79
	s_waitcnt lgkmcnt(0)
	v_add_f32_e32 v79, v79, v96
	v_fmamk_f32 v79, v79, 0x3a800000, v78
	v_cmp_gt_f32_e32 vcc, s1, v79
	v_mul_f32_e32 v96, 0x4b800000, v79
	s_nop 0
	v_cndmask_b32_e32 v79, v79, v96, vcc
	v_rsq_f32_e32 v79, v79
	s_nop 0
	v_mul_f32_e32 v96, 0x45800000, v79
	v_cndmask_b32_e32 v79, v79, v96, vcc
	v_mul_f32_e32 v80, v80, v79
	v_mul_f32_e32 v81, v81, v79
	s_waitcnt vmcnt(3)
	v_mul_f32_e32 v80, v40, v80
	v_mul_f32_e32 v81, v41, v81
	v_cvt_pk_bf16_f32 v80, v80, v81
	v_mul_f32_e32 v81, v82, v79
	v_mul_f32_e32 v81, v42, v81
	v_mul_f32_e32 v82, v83, v79
	v_mul_f32_e32 v82, v43, v82
	v_cvt_pk_bf16_f32 v81, v81, v82
	global_store_dwordx2 v[68:69], v[80:81], off
	v_mul_f32_e32 v80, v84, v79
	v_mul_f32_e32 v81, v85, v79
	s_waitcnt vmcnt(3)
	v_mul_f32_e32 v80, v36, v80
	v_mul_f32_e32 v81, v37, v81
	v_cvt_pk_bf16_f32 v80, v80, v81
	v_mul_f32_e32 v81, v86, v79
	v_mul_f32_e32 v81, v38, v81
	v_mul_f32_e32 v82, v87, v79
	v_mul_f32_e32 v82, v39, v82
	v_cvt_pk_bf16_f32 v81, v81, v82
	global_store_dwordx2 v[68:69], v[80:81], off offset:512
	v_mul_f32_e32 v80, v88, v79
	v_mul_f32_e32 v81, v89, v79
	s_waitcnt vmcnt(3)
	v_mul_f32_e32 v80, v28, v80
	v_mul_f32_e32 v81, v29, v81
	v_cvt_pk_bf16_f32 v80, v80, v81
	v_mul_f32_e32 v81, v90, v79
	v_mul_f32_e32 v81, v30, v81
	v_mul_f32_e32 v82, v91, v79
	v_mul_f32_e32 v82, v31, v82
	v_cvt_pk_bf16_f32 v81, v81, v82
	global_store_dwordx2 v[68:69], v[80:81], off offset:1024
	v_mul_f32_e32 v80, v92, v79
	v_mul_f32_e32 v81, v93, v79
	s_waitcnt vmcnt(3)
	v_mul_f32_e32 v80, v20, v80
	v_mul_f32_e32 v81, v21, v81
	v_cvt_pk_bf16_f32 v80, v80, v81
	v_mul_f32_e32 v81, v94, v79
	v_mul_f32_e32 v81, v22, v81
	v_mul_f32_e32 v79, v95, v79
	v_mul_f32_e32 v79, v23, v79
	v_cvt_pk_bf16_f32 v81, v81, v79
	global_store_dwordx2 v[68:69], v[80:81], off offset:1536
	v_pk_mul_f32 v[80:81], v[62:63], v[62:63]
	v_pk_mul_f32 v[82:83], v[60:61], v[60:61]
	v_mul_f32_e32 v79, v48, v48
	v_pk_mov_b32 v[84:85], v[82:83], v[80:81] op_sel:[1,0]
	v_mov_b32_e32 v83, v81
	v_pk_add_f32 v[80:81], v[84:85], v[82:83]
	v_pk_mul_f32 v[82:83], v[58:59], v[58:59]
	v_pk_mul_f32 v[84:85], v[56:57], v[56:57]
	v_pk_add_f32 v[80:81], v[80:81], v[80:81] op_sel:[0,1] op_sel_hi:[1,0]
	v_pk_mov_b32 v[86:87], v[84:85], v[82:83] op_sel:[1,0]
	v_mov_b32_e32 v85, v83
	v_pk_add_f32 v[82:83], v[86:87], v[84:85]
	v_mul_f32_e32 v84, v49, v49
	v_pk_add_f32 v[82:83], v[82:83], v[82:83] op_sel:[0,1] op_sel_hi:[1,0]
	v_mov_b32_e32 v81, v79
	v_mov_b32_e32 v83, v84
	v_pk_add_f32 v[80:81], v[80:81], v[82:83]
	v_mul_f32_e32 v82, v53, v53
	v_mul_f32_e32 v85, v50, v50
	v_pk_fma_f32 v[82:83], v[52:53], v[52:53], v[82:83] op_sel_hi:[1,1,0]
	v_mul_f32_e32 v84, v55, v55
	v_mul_f32_e32 v86, v51, v51
	v_mov_b32_e32 v83, v85
	v_pk_fma_f32 v[84:85], v[54:55], v[54:55], v[84:85] op_sel_hi:[1,1,0]
	s_nop 0
	v_mov_b32_e32 v85, v86
	v_pk_add_f32 v[82:83], v[82:83], v[84:85]
	s_nop 0
	v_pk_add_f32 v[80:81], v[80:81], v[82:83]
	s_nop 0
	v_add_f32_e32 v79, v80, v81
	ds_bpermute_b32 v80, v72, v79
	s_waitcnt lgkmcnt(0)
	v_add_f32_e32 v79, v79, v80
	ds_bpermute_b32 v80, v73, v79
	s_waitcnt lgkmcnt(0)
	v_add_f32_e32 v79, v79, v80
	ds_bpermute_b32 v80, v74, v79
	s_waitcnt lgkmcnt(0)
	v_add_f32_e32 v79, v79, v80
	ds_bpermute_b32 v80, v75, v79
	s_waitcnt lgkmcnt(0)
	v_add_f32_e32 v79, v79, v80
	ds_bpermute_b32 v80, v76, v79
	s_waitcnt lgkmcnt(0)
	v_add_f32_e32 v79, v79, v80
	ds_bpermute_b32 v80, v77, v79
	s_waitcnt lgkmcnt(0)
	v_add_f32_e32 v79, v79, v80
	v_fmamk_f32 v79, v79, 0x3a800000, v78
	v_cmp_gt_f32_e32 vcc, s1, v79
	v_mul_f32_e32 v80, 0x4b800000, v79
	s_nop 0
	v_cndmask_b32_e32 v79, v79, v80, vcc
	v_rsq_f32_e32 v79, v79
	s_nop 0
	v_mul_f32_e32 v80, 0x45800000, v79
	v_cndmask_b32_e32 v79, v79, v80, vcc
	v_mul_f32_e32 v48, v48, v79
	v_mul_f32_e32 v49, v49, v79
	v_mul_f32_e32 v52, v52, v79
	v_mul_f32_e32 v53, v53, v79
	v_mul_f32_e32 v48, v20, v48
	v_mul_f32_e32 v49, v21, v49
	v_mul_f32_e32 v52, v28, v52
	v_mul_f32_e32 v53, v29, v53
	v_cvt_pk_bf16_f32 v48, v48, v49
	v_mul_f32_e32 v49, v50, v79
	v_cvt_pk_bf16_f32 v52, v52, v53
	v_mul_f32_e32 v53, v54, v79
	v_mul_f32_e32 v49, v22, v49
	v_mul_f32_e32 v50, v51, v79
	v_mul_f32_e32 v53, v30, v53
	v_mul_f32_e32 v54, v55, v79
	v_mul_f32_e32 v50, v23, v50
	v_cvt_pk_bf16_f32 v49, v49, v50
	v_mul_f32_e32 v54, v31, v54
	v_cvt_pk_bf16_f32 v53, v53, v54
	global_store_dwordx2 v[68:69], v[48:49], off offset:3584
	v_pk_mul_f32 v[48:49], v[46:47], v[46:47]
	v_pk_mul_f32 v[50:51], v[44:45], v[44:45]
	global_store_dwordx2 v[68:69], v[52:53], off offset:3072
	v_pk_mov_b32 v[52:53], v[50:51], v[48:49] op_sel:[1,0]
	v_mov_b32_e32 v51, v49
	v_pk_add_f32 v[48:49], v[52:53], v[50:51]
	v_pk_mul_f32 v[50:51], v[34:35], v[34:35]
	v_pk_mul_f32 v[52:53], v[32:33], v[32:33]
	v_pk_add_f32 v[48:49], v[48:49], v[48:49] op_sel:[0,1] op_sel_hi:[1,0]
	v_pk_mov_b32 v[54:55], v[52:53], v[50:51] op_sel:[1,0]
	v_mov_b32_e32 v53, v51
	v_pk_add_f32 v[50:51], v[54:55], v[52:53]
	v_mul_f32_e32 v52, v16, v16
	v_mul_f32_e32 v53, v17, v17
	v_pk_add_f32 v[50:51], v[50:51], v[50:51] op_sel:[0,1] op_sel_hi:[1,0]
	v_mov_b32_e32 v49, v52
	v_mov_b32_e32 v51, v53
	v_pk_add_f32 v[48:49], v[48:49], v[50:51]
	v_mul_f32_e32 v50, v25, v25
	v_mul_f32_e32 v52, v27, v27
	v_mul_f32_e32 v54, v18, v18
	v_mul_f32_e32 v55, v19, v19
	v_pk_fma_f32 v[50:51], v[24:25], v[24:25], v[50:51] op_sel_hi:[1,1,0]
	v_pk_fma_f32 v[52:53], v[26:27], v[26:27], v[52:53] op_sel_hi:[1,1,0]
	v_mov_b32_e32 v51, v54
	v_mov_b32_e32 v53, v55
	v_pk_add_f32 v[50:51], v[50:51], v[52:53]
	v_mul_f32_e32 v60, v60, v79
	v_pk_add_f32 v[48:49], v[48:49], v[50:51]
	v_mul_f32_e32 v61, v61, v79
	v_add_f32_e32 v48, v48, v49
	ds_bpermute_b32 v49, v72, v48
	v_mul_f32_e32 v56, v56, v79
	v_mul_f32_e32 v57, v57, v79
	v_mul_f32_e32 v60, v40, v60
	v_mul_f32_e32 v61, v41, v61
	s_waitcnt lgkmcnt(0)
	v_add_f32_e32 v48, v48, v49
	ds_bpermute_b32 v49, v73, v48
	v_mul_f32_e32 v56, v36, v56
	v_mul_f32_e32 v57, v37, v57
	v_cvt_pk_bf16_f32 v60, v60, v61
	v_mul_f32_e32 v61, v62, v79
	s_waitcnt lgkmcnt(0)
	v_add_f32_e32 v48, v48, v49
	ds_bpermute_b32 v49, v74, v48
	v_cvt_pk_bf16_f32 v56, v56, v57
	v_mul_f32_e32 v57, v58, v79
	v_mul_f32_e32 v61, v42, v61
	v_mul_f32_e32 v62, v63, v79
	s_waitcnt lgkmcnt(0)
	v_add_f32_e32 v48, v48, v49
	ds_bpermute_b32 v49, v75, v48
	v_mul_f32_e32 v57, v38, v57
	v_mul_f32_e32 v58, v59, v79
	v_mul_f32_e32 v62, v43, v62
	v_cvt_pk_bf16_f32 v61, v61, v62
	s_waitcnt lgkmcnt(0)
	v_add_f32_e32 v48, v48, v49
	ds_bpermute_b32 v49, v76, v48
	global_store_dwordx2 v[68:69], v[60:61], off offset:2048
	v_mul_f32_e32 v58, v39, v58
	v_cvt_pk_bf16_f32 v57, v57, v58
	global_store_dwordx2 v[68:69], v[56:57], off offset:2560
	s_waitcnt lgkmcnt(0)
	v_add_f32_e32 v48, v48, v49
	ds_bpermute_b32 v49, v77, v48
	s_waitcnt lgkmcnt(0)
	v_add_f32_e32 v48, v48, v49
	v_fmamk_f32 v48, v48, 0x3a800000, v78
	v_cmp_gt_f32_e32 vcc, s1, v48
	v_mul_f32_e32 v49, 0x4b800000, v48
	s_nop 0
	v_cndmask_b32_e32 v48, v48, v49, vcc
	v_rsq_f32_e32 v48, v48
	s_nop 0
	v_mul_f32_e32 v49, 0x45800000, v48
	v_cndmask_b32_e32 v48, v48, v49, vcc
	v_mul_f32_e32 v44, v44, v48
	v_mul_f32_e32 v45, v45, v48
	v_mul_f32_e32 v44, v40, v44
	v_mul_f32_e32 v45, v41, v45
	v_mul_f32_e32 v16, v16, v48
	v_mul_f32_e32 v17, v17, v48
	v_cvt_pk_bf16_f32 v44, v44, v45
	v_mul_f32_e32 v45, v46, v48
	v_mul_f32_e32 v46, v47, v48
	v_mul_f32_e32 v24, v24, v48
	v_mul_f32_e32 v25, v25, v48
	v_mul_f32_e32 v16, v20, v16
	v_mul_f32_e32 v17, v21, v17
	v_mul_f32_e32 v45, v42, v45
	v_mul_f32_e32 v46, v43, v46
	v_mul_f32_e32 v24, v28, v24
	v_mul_f32_e32 v25, v29, v25
	v_cvt_pk_bf16_f32 v16, v16, v17
	v_mul_f32_e32 v17, v18, v48
	v_cvt_pk_bf16_f32 v45, v45, v46
	v_add_co_u32_e32 v46, vcc, s7, v68
	v_cvt_pk_bf16_f32 v24, v24, v25
	v_mul_f32_e32 v25, v26, v48
	v_mul_f32_e32 v17, v22, v17
	v_mul_f32_e32 v18, v19, v48
	v_addc_co_u32_e32 v47, vcc, 0, v69, vcc
	v_mul_f32_e32 v25, v30, v25
	v_mul_f32_e32 v26, v27, v48
	v_mul_f32_e32 v18, v23, v18
	v_cvt_pk_bf16_f32 v17, v17, v18
	v_mul_f32_e32 v26, v31, v26
	v_cvt_pk_bf16_f32 v25, v25, v26
	global_store_dwordx2 v[46:47], v[16:17], off offset:1536
	v_pk_mul_f32 v[16:17], v[14:15], v[14:15]
	v_pk_mul_f32 v[18:19], v[12:13], v[12:13]
	global_store_dwordx2 v[46:47], v[24:25], off offset:1024
	v_pk_mov_b32 v[24:25], v[18:19], v[16:17] op_sel:[1,0]
	v_mov_b32_e32 v19, v17
	v_pk_add_f32 v[16:17], v[24:25], v[18:19]
	v_pk_mul_f32 v[18:19], v[10:11], v[10:11]
	v_pk_mul_f32 v[24:25], v[8:9], v[8:9]
	v_pk_add_f32 v[16:17], v[16:17], v[16:17] op_sel:[0,1] op_sel_hi:[1,0]
	v_pk_mov_b32 v[26:27], v[24:25], v[18:19] op_sel:[1,0]
	v_mov_b32_e32 v25, v19
	v_pk_add_f32 v[18:19], v[26:27], v[24:25]
	v_mul_f32_e32 v24, v0, v0
	v_mul_f32_e32 v25, v1, v1
	v_pk_add_f32 v[18:19], v[18:19], v[18:19] op_sel:[0,1] op_sel_hi:[1,0]
	v_mov_b32_e32 v17, v24
	v_mov_b32_e32 v19, v25
	v_pk_add_f32 v[16:17], v[16:17], v[18:19]
	v_mul_f32_e32 v18, v5, v5
	v_mul_f32_e32 v24, v7, v7
	v_mul_f32_e32 v26, v2, v2
	v_mul_f32_e32 v27, v3, v3
	v_pk_fma_f32 v[18:19], v[4:5], v[4:5], v[18:19] op_sel_hi:[1,1,0]
	v_pk_fma_f32 v[24:25], v[6:7], v[6:7], v[24:25] op_sel_hi:[1,1,0]
	v_mov_b32_e32 v19, v26
	v_mov_b32_e32 v25, v27
	v_pk_add_f32 v[18:19], v[18:19], v[24:25]
	v_mul_f32_e32 v32, v32, v48
	v_pk_add_f32 v[16:17], v[16:17], v[18:19]
	v_mul_f32_e32 v33, v33, v48
	v_add_f32_e32 v16, v16, v17
	ds_bpermute_b32 v17, v72, v16
	v_mul_f32_e32 v32, v36, v32
	v_mul_f32_e32 v33, v37, v33
	v_cvt_pk_bf16_f32 v32, v32, v33
	v_mul_f32_e32 v33, v34, v48
	s_waitcnt lgkmcnt(0)
	v_add_f32_e32 v16, v16, v17
	ds_bpermute_b32 v17, v73, v16
	v_mul_f32_e32 v33, v38, v33
	v_mul_f32_e32 v34, v35, v48
	v_lshl_add_u64 v[68:69], v[68:69], 0, s[2:3]
	global_store_dwordx2 v[46:47], v[44:45], off
	s_waitcnt lgkmcnt(0)
	v_add_f32_e32 v16, v16, v17
	ds_bpermute_b32 v17, v74, v16
	v_mul_f32_e32 v34, v39, v34
	v_cvt_pk_bf16_f32 v33, v33, v34
	global_store_dwordx2 v[46:47], v[32:33], off offset:512
	s_waitcnt lgkmcnt(0)
	v_add_f32_e32 v16, v16, v17
	ds_bpermute_b32 v17, v75, v16
	s_waitcnt lgkmcnt(0)
	v_add_f32_e32 v16, v16, v17
	ds_bpermute_b32 v17, v76, v16
	s_waitcnt lgkmcnt(0)
	v_add_f32_e32 v16, v16, v17
	ds_bpermute_b32 v17, v77, v16
	s_waitcnt lgkmcnt(0)
	v_add_f32_e32 v16, v16, v17
	v_fmamk_f32 v16, v16, 0x3a800000, v78
	v_cmp_gt_f32_e32 vcc, s1, v16
	v_mul_f32_e32 v17, 0x4b800000, v16
	s_nop 0
	v_cndmask_b32_e32 v16, v16, v17, vcc
	v_rsq_f32_e32 v16, v16
	s_nop 0
	v_mul_f32_e32 v17, 0x45800000, v16
	v_cndmask_b32_e32 v16, v16, v17, vcc
	v_mul_f32_e32 v12, v12, v16
	v_mul_f32_e32 v13, v13, v16
	v_mul_f32_e32 v8, v8, v16
	v_mul_f32_e32 v9, v9, v16
	v_mul_f32_e32 v4, v4, v16
	v_mul_f32_e32 v5, v5, v16
	v_mul_f32_e32 v0, v0, v16
	v_mul_f32_e32 v1, v1, v16
	v_mul_f32_e32 v12, v40, v12
	v_mul_f32_e32 v13, v41, v13
	v_mul_f32_e32 v8, v36, v8
	v_mul_f32_e32 v9, v37, v9
	v_mul_f32_e32 v4, v28, v4
	v_mul_f32_e32 v5, v29, v5
	v_mul_f32_e32 v0, v20, v0
	v_mul_f32_e32 v1, v21, v1
	v_cvt_pk_bf16_f32 v12, v12, v13
	v_mul_f32_e32 v13, v14, v16
	v_cvt_pk_bf16_f32 v8, v8, v9
	v_mul_f32_e32 v9, v10, v16
	v_cvt_pk_bf16_f32 v4, v4, v5
	v_mul_f32_e32 v5, v6, v16
	v_cvt_pk_bf16_f32 v0, v0, v1
	v_mul_f32_e32 v1, v2, v16
	v_mul_f32_e32 v13, v42, v13
	v_mul_f32_e32 v14, v15, v16
	v_mul_f32_e32 v9, v38, v9
	v_mul_f32_e32 v10, v11, v16
	v_mul_f32_e32 v5, v30, v5
	v_mul_f32_e32 v6, v7, v16
	v_mul_f32_e32 v1, v22, v1
	v_mul_f32_e32 v2, v3, v16
	v_mul_f32_e32 v14, v43, v14
	v_cvt_pk_bf16_f32 v13, v13, v14
	global_store_dwordx2 v[46:47], v[12:13], off offset:2048
	v_mul_f32_e32 v10, v39, v10
	v_cvt_pk_bf16_f32 v9, v9, v10
	global_store_dwordx2 v[46:47], v[8:9], off offset:2560
	v_mul_f32_e32 v6, v31, v6
	v_cvt_pk_bf16_f32 v5, v5, v6
	global_store_dwordx2 v[46:47], v[4:5], off offset:3072
	v_mul_f32_e32 v2, v23, v2
	v_cvt_pk_bf16_f32 v1, v1, v2
	global_store_dwordx2 v[46:47], v[0:1], off offset:3584
	s_cbranch_scc0 .LBB0_561

.LBB0_1708:
	s_or_b64 exec, exec, s[30:31]
	v_readlane_b32 s0, v251, 31
	v_readlane_b32 s1, v251, 32
	v_mov_b32_e32 v76, v184
	s_waitcnt lgkmcnt(0)
	v_cndmask_b32_e64 v0, 0, 1, s[0:1]
	s_barrier
	v_cmp_ne_u32_e64 s[6:7], 1, v0
	s_andn2_b64 vcc, exec, s[0:1]
	v_ashrrev_i32_e32 v77, 31, v76
	s_cbranch_vccnz .LBB0_1711
	s_bfe_u32 s98, s72, 0x20002
	s_cmp_eq_u32 s98, 3
	s_cbranch_scc1 .LBB0_1711
	s_movk_i32 s100, 0x2000
	s_movk_i32 s101, 0x4000
	s_cmp_eq_u32 s98, 1
	s_cselect_b32 s100, 8, s100
	s_cselect_b32 s101, 0x1ff8, s101
	s_cmp_eq_u32 s98, 2
	s_cselect_b32 s101, 4, s101
	s_cmp_eq_u32 s98, 0
	s_cselect_b32 s98, 2, 3
	s_mov_b32 s99, 0
	v_and_b32_e32 v0, 64, v198
	v_add_u32_e32 v0, 64, v0
	v_xor_b32_e32 v1, 1, v198
	v_cmp_lt_i32_e32 vcc, v1, v0
	s_ashr_i32 s73, s72, 31
	s_lshl_b32 s8, s94, 5
	v_cndmask_b32_e32 v1, v198, v1, vcc
	v_lshlrev_b32_e32 v86, 2, v1
	v_xor_b32_e32 v1, 2, v198
	v_cmp_lt_i32_e32 vcc, v1, v0
	s_lshl_b64 s[0:1], s[72:73], 11
	s_add_u32 s0, s54, s0
	v_cndmask_b32_e32 v1, v198, v1, vcc
	v_lshlrev_b32_e32 v87, 2, v1
	v_xor_b32_e32 v1, 4, v198
	v_cmp_lt_i32_e32 vcc, v1, v0
	s_addc_u32 s1, s55, s1
	v_lshl_add_u64 v[2:3], v[76:77], 3, s[0:1]
	v_cndmask_b32_e32 v1, v198, v1, vcc
	v_lshlrev_b32_e32 v88, 2, v1
	v_xor_b32_e32 v1, 8, v198
	v_cmp_lt_i32_e32 vcc, v1, v0
	s_mov_b64 s[0:1], 0x30d4000
	s_ashr_i32 s9, s8, 31
	v_cndmask_b32_e32 v1, v198, v1, vcc
	v_lshlrev_b32_e32 v89, 2, v1
	v_xor_b32_e32 v1, 16, v198
	v_cmp_lt_i32_e32 vcc, v1, v0
	v_lshl_add_u64 v[80:81], v[2:3], 0, s[0:1]
	s_lshl_b64 s[10:11], s[8:9], 11
	v_cndmask_b32_e32 v1, v198, v1, vcc
	v_lshlrev_b32_e32 v90, 2, v1
	v_xor_b32_e32 v1, 32, v198
	v_cmp_lt_i32_e32 vcc, v1, v0
	s_lshl_b64 s[0:1], s[72:73], 12
	v_readlane_b32 s12, v252, 48
	v_cndmask_b32_e32 v0, v198, v1, vcc
	s_add_u32 s0, s52, s0
	v_lshlrev_b32_e32 v91, 2, v0
	v_lshlrev_b64 v[0:1], 4, v[76:77]
	v_readlane_b32 s13, v252, 49
	v_readlane_b32 s14, v252, 50
	v_readlane_b32 s15, v252, 51
	v_readlane_b32 s22, v252, 58
	v_readlane_b32 s23, v252, 59
	s_addc_u32 s1, s53, s1
	v_lshl_add_u64 v[82:83], s[0:1], 0, v[0:1]
	v_lshl_add_u64 v[78:79], s[22:23], 0, v[0:1]
	s_lshl_b64 s[12:13], s[8:9], 12
	s_movk_i32 s9, 0x1000
	v_mov_b32_e32 v92, 0x358637bd
	s_mov_b32 s14, 0x800000
	s_mov_b32 s15, s72
	v_readlane_b32 s16, v252, 52
	v_readlane_b32 s17, v252, 53
	v_readlane_b32 s18, v252, 54
	v_readlane_b32 s19, v252, 55
	v_readlane_b32 s20, v252, 56
	v_readlane_b32 s21, v252, 57
	v_readlane_b32 s24, v252, 60
	v_readlane_b32 s25, v252, 61
	v_readlane_b32 s26, v252, 62
	v_readlane_b32 s27, v252, 63
.LBB0_1710:
	v_add_co_u32_e32 v32, vcc, 0x1000, v82
	global_load_dwordx4 v[28:31], v[82:83], off
	global_load_dwordx4 v[24:27], v[82:83], off offset:1024
	global_load_dwordx4 v[20:23], v[82:83], off offset:2048
	global_load_dwordx4 v[16:19], v[82:83], off offset:3072
	v_addc_co_u32_e32 v33, vcc, 0, v83, vcc
	v_add_co_u32_e32 v34, vcc, 0x2000, v82
	global_load_dwordx4 v[12:15], v[78:79], off
	global_load_dwordx4 v[8:11], v[78:79], off offset:1024
	global_load_dwordx4 v[4:7], v[78:79], off offset:2048
	global_load_dwordx4 v[0:3], v[78:79], off offset:3072
	global_load_dwordx4 v[94:97], v[32:33], off
	global_load_dwordx4 v[72:75], v[32:33], off offset:1024
	global_load_dwordx4 v[64:67], v[32:33], off offset:3072
	global_load_dwordx4 v[68:71], v[32:33], off offset:2048
	v_addc_co_u32_e32 v35, vcc, 0, v83, vcc
	global_load_dwordx4 v[60:63], v[34:35], off
	global_load_dwordx4 v[56:59], v[34:35], off offset:1024
	global_load_dwordx4 v[48:51], v[34:35], off offset:3072
	global_load_dwordx4 v[52:55], v[34:35], off offset:2048
	v_add_co_u32_e32 v36, vcc, 0x3000, v82
	v_add_co_u32_e64 v84, s[0:1], s9, v80
	s_nop 0
	v_addc_co_u32_e32 v37, vcc, 0, v83, vcc
	global_load_dwordx4 v[44:47], v[36:37], off
	global_load_dwordx4 v[40:43], v[36:37], off offset:1024
	global_load_dwordx4 v[32:35], v[36:37], off offset:3072
	s_nop 0
	global_load_dwordx4 v[36:39], v[36:37], off offset:2048
	v_addc_co_u32_e64 v85, s[0:1], 0, v81, s[0:1]
	s_add_i32 s99, s99, 1
	s_cmp_eq_u32 s99, 2
	s_cselect_b32 s8, s101, s100
	s_cmp_ge_u32 s99, s98
	s_cselect_b32 s8, 0x4000, s8
	s_lshl_b32 s12, s8, 12
	s_mov_b32 s13, 0
	s_lshl_b32 s10, s8, 11
	s_mov_b32 s11, 0
	s_add_i32 s15, s15, s8
	s_cmpk_gt_i32 s15, 0x3fff
	v_lshl_add_u64 v[82:83], v[82:83], 0, s[12:13]
	s_waitcnt vmcnt(0)
	v_pk_mul_f32 v[98:99], v[30:31], v[30:31]
	v_pk_mul_f32 v[100:101], v[28:29], v[28:29]
	v_pk_mul_f32 v[102:103], v[26:27], v[26:27]
	v_pk_mul_f32 v[104:105], v[24:25], v[24:25]
	v_mul_f32_e32 v109, v18, v18
	v_mul_f32_e32 v106, v21, v21
	v_mul_f32_e32 v108, v23, v23
	v_mul_f32_e32 v112, v19, v19
	v_pk_mov_b32 v[110:111], v[100:101], v[98:99] op_sel:[1,0]
	v_mov_b32_e32 v101, v99
	v_pk_mov_b32 v[98:99], v[104:105], v[102:103] op_sel:[1,0]
	v_mov_b32_e32 v105, v103
	v_pk_fma_f32 v[102:103], v[20:21], v[20:21], v[106:107] op_sel_hi:[1,1,0]
	v_pk_fma_f32 v[106:107], v[22:23], v[22:23], v[108:109] op_sel_hi:[1,1,0]
	v_pk_add_f32 v[100:101], v[110:111], v[100:101]
	v_pk_add_f32 v[98:99], v[98:99], v[104:105]
	v_mov_b32_e32 v103, v109
	v_mov_b32_e32 v107, v112
	v_pk_mul_f32 v[104:105], v[96:97], v[96:97]
	v_pk_mul_f32 v[108:109], v[94:95], v[94:95]
	v_pk_mul_f32 v[110:111], v[74:75], v[74:75]
	v_pk_mul_f32 v[112:113], v[72:73], v[72:73]
	v_mul_f32_e32 v114, v69, v69
	v_mul_f32_e32 v116, v71, v71
	v_mul_f32_e32 v93, v16, v16
	v_mul_f32_e32 v125, v17, v17
	v_mul_f32_e32 v127, v66, v66
	v_mul_f32_e32 v128, v67, v67
	v_pk_add_f32 v[100:101], v[100:101], v[100:101] op_sel:[0,1] op_sel_hi:[1,0]
	v_pk_add_f32 v[98:99], v[98:99], v[98:99] op_sel:[0,1] op_sel_hi:[1,0]
	v_pk_add_f32 v[102:103], v[102:103], v[106:107]
	v_pk_mov_b32 v[106:107], v[108:109], v[104:105] op_sel:[1,0]
	v_mov_b32_e32 v109, v105
	v_pk_mov_b32 v[104:105], v[112:113], v[110:111] op_sel:[1,0]
	v_mov_b32_e32 v113, v111
	v_pk_fma_f32 v[110:111], v[68:69], v[68:69], v[114:115] op_sel_hi:[1,1,0]
	v_pk_fma_f32 v[114:115], v[70:71], v[70:71], v[116:117] op_sel_hi:[1,1,0]
	v_pk_mul_f32 v[116:117], v[62:63], v[62:63]
	v_pk_mul_f32 v[118:119], v[60:61], v[60:61]
	v_pk_mul_f32 v[120:121], v[58:59], v[58:59]
	v_pk_mul_f32 v[122:123], v[56:57], v[56:57]
	v_mul_f32_e32 v124, v53, v53
	v_mul_f32_e32 v126, v55, v55
	v_mov_b32_e32 v101, v93
	v_mov_b32_e32 v99, v125
	v_pk_add_f32 v[106:107], v[106:107], v[108:109]
	v_pk_add_f32 v[104:105], v[104:105], v[112:113]
	v_mov_b32_e32 v111, v127
	v_mov_b32_e32 v115, v128
	v_pk_mov_b32 v[108:109], v[118:119], v[116:117] op_sel:[1,0]
	v_mov_b32_e32 v119, v117
	v_pk_mov_b32 v[112:113], v[122:123], v[120:121] op_sel:[1,0]
	v_mov_b32_e32 v123, v121
	v_pk_fma_f32 v[116:117], v[52:53], v[52:53], v[124:125] op_sel_hi:[1,1,0]
	v_pk_fma_f32 v[120:121], v[54:55], v[54:55], v[126:127] op_sel_hi:[1,1,0]
	v_pk_mul_f32 v[124:125], v[46:47], v[46:47]
	v_pk_mul_f32 v[126:127], v[44:45], v[44:45]
	v_pk_mul_f32 v[128:129], v[42:43], v[42:43]
	v_pk_mul_f32 v[130:131], v[40:41], v[40:41]
	v_mul_f32_e32 v133, v64, v64
	v_mul_f32_e32 v135, v65, v65
	v_mul_f32_e32 v138, v50, v50
	v_mul_f32_e32 v139, v51, v51
	v_pk_add_f32 v[98:99], v[100:101], v[98:99]
	v_pk_add_f32 v[100:101], v[106:107], v[106:107] op_sel:[0,1] op_sel_hi:[1,0]
	v_pk_add_f32 v[104:105], v[104:105], v[104:105] op_sel:[0,1] op_sel_hi:[1,0]
	v_pk_add_f32 v[106:107], v[110:111], v[114:115]
	v_pk_add_f32 v[108:109], v[108:109], v[118:119]
	v_pk_add_f32 v[110:111], v[112:113], v[122:123]
	v_pk_mov_b32 v[112:113], v[126:127], v[124:125] op_sel:[1,0]
	v_mov_b32_e32 v127, v125
	v_pk_mov_b32 v[114:115], v[130:131], v[128:129] op_sel:[1,0]
	v_mov_b32_e32 v131, v129
	v_mul_f32_e32 v136, v48, v48
	v_mul_f32_e32 v137, v49, v49
	v_mul_f32_e32 v132, v37, v37
	v_mul_f32_e32 v134, v39, v39
	v_mov_b32_e32 v117, v138
	v_mov_b32_e32 v121, v139
	v_pk_add_f32 v[98:99], v[98:99], v[102:103]
	v_mov_b32_e32 v101, v133
	v_mov_b32_e32 v105, v135
	v_pk_add_f32 v[102:103], v[108:109], v[108:109] op_sel:[0,1] op_sel_hi:[1,0]
	v_pk_add_f32 v[108:109], v[110:111], v[110:111] op_sel:[0,1] op_sel_hi:[1,0]
	v_pk_add_f32 v[112:113], v[112:113], v[126:127]
	v_pk_add_f32 v[114:115], v[114:115], v[130:131]
	v_mul_f32_e32 v93, v32, v32
	v_mul_f32_e32 v140, v33, v33
	v_mul_f32_e32 v141, v34, v34
	v_mul_f32_e32 v142, v35, v35
	v_pk_fma_f32 v[118:119], v[36:37], v[36:37], v[132:133] op_sel_hi:[1,1,0]
	v_pk_fma_f32 v[122:123], v[38:39], v[38:39], v[134:135] op_sel_hi:[1,1,0]
	v_pk_add_f32 v[110:111], v[116:117], v[120:121]
	v_add_f32_e32 v116, v98, v99
	v_pk_add_f32 v[98:99], v[100:101], v[104:105]
	v_mov_b32_e32 v103, v136
	v_mov_b32_e32 v109, v137
	v_pk_add_f32 v[100:101], v[112:113], v[112:113] op_sel:[0,1] op_sel_hi:[1,0]
	v_pk_add_f32 v[104:105], v[114:115], v[114:115] op_sel:[0,1] op_sel_hi:[1,0]
	v_mov_b32_e32 v119, v141
	v_mov_b32_e32 v123, v142
	ds_bpermute_b32 v114, v86, v116
	v_pk_add_f32 v[98:99], v[98:99], v[106:107]
	v_pk_add_f32 v[102:103], v[102:103], v[108:109]
	v_mov_b32_e32 v101, v93
	v_mov_b32_e32 v105, v140
	v_pk_add_f32 v[112:113], v[118:119], v[122:123]
	v_add_f32_e32 v93, v98, v99
	v_pk_add_f32 v[98:99], v[102:103], v[110:111]
	v_pk_add_f32 v[100:101], v[100:101], v[104:105]
	ds_bpermute_b32 v102, v86, v93
	v_add_f32_e32 v103, v98, v99
	v_pk_add_f32 v[98:99], v[100:101], v[112:113]
	ds_bpermute_b32 v100, v86, v103
	v_add_f32_e32 v98, v98, v99
	ds_bpermute_b32 v99, v86, v98
	s_waitcnt lgkmcnt(3)
	v_add_f32_e32 v101, v116, v114
	ds_bpermute_b32 v104, v87, v101
	s_waitcnt lgkmcnt(3)
	v_add_f32_e32 v93, v93, v102
	ds_bpermute_b32 v102, v87, v93
	s_waitcnt lgkmcnt(3)
	v_add_f32_e32 v100, v103, v100
	ds_bpermute_b32 v103, v87, v100
	s_waitcnt lgkmcnt(3)
	v_add_f32_e32 v98, v98, v99
	ds_bpermute_b32 v99, v87, v98
	s_waitcnt lgkmcnt(3)
	v_add_f32_e32 v101, v101, v104
	ds_bpermute_b32 v104, v88, v101
	s_waitcnt lgkmcnt(3)
	v_add_f32_e32 v93, v93, v102
	ds_bpermute_b32 v102, v88, v93
	s_waitcnt lgkmcnt(3)
	v_add_f32_e32 v100, v100, v103
	ds_bpermute_b32 v103, v88, v100
	s_waitcnt lgkmcnt(3)
	v_add_f32_e32 v98, v98, v99
	ds_bpermute_b32 v99, v88, v98
	s_waitcnt lgkmcnt(3)
	v_add_f32_e32 v101, v101, v104
	ds_bpermute_b32 v104, v89, v101
	s_waitcnt lgkmcnt(3)
	v_add_f32_e32 v93, v93, v102
	ds_bpermute_b32 v102, v89, v93
	s_waitcnt lgkmcnt(3)
	v_add_f32_e32 v100, v100, v103
	ds_bpermute_b32 v103, v89, v100
	s_waitcnt lgkmcnt(3)
	v_add_f32_e32 v98, v98, v99
	ds_bpermute_b32 v99, v89, v98
	s_waitcnt lgkmcnt(3)
	v_add_f32_e32 v101, v101, v104
	ds_bpermute_b32 v104, v90, v101
	s_waitcnt lgkmcnt(3)
	v_add_f32_e32 v93, v93, v102
	ds_bpermute_b32 v102, v90, v93
	s_waitcnt lgkmcnt(3)
	v_add_f32_e32 v100, v100, v103
	ds_bpermute_b32 v103, v90, v100
	s_waitcnt lgkmcnt(3)
	v_add_f32_e32 v98, v98, v99
	ds_bpermute_b32 v99, v90, v98
	s_waitcnt lgkmcnt(3)
	v_add_f32_e32 v101, v101, v104
	ds_bpermute_b32 v104, v91, v101
	s_waitcnt lgkmcnt(3)
	v_add_f32_e32 v93, v93, v102
	ds_bpermute_b32 v102, v91, v93
	s_waitcnt lgkmcnt(3)
	v_add_f32_e32 v100, v100, v103
	ds_bpermute_b32 v103, v91, v100
	s_waitcnt lgkmcnt(3)
	v_add_f32_e32 v98, v98, v99
	ds_bpermute_b32 v99, v91, v98
	s_waitcnt lgkmcnt(3)
	v_add_f32_e32 v101, v101, v104
	v_fmamk_f32 v101, v101, 0x3a800000, v92
	v_mul_f32_e32 v104, 0x4b800000, v101
	s_waitcnt lgkmcnt(2)
	v_add_f32_e32 v93, v93, v102
	v_cmp_gt_f32_e64 s[0:1], s14, v101
	v_fmamk_f32 v93, v93, 0x3a800000, v92
	s_waitcnt lgkmcnt(1)
	v_add_f32_e32 v100, v100, v103
	v_cndmask_b32_e64 v101, v101, v104, s[0:1]
	v_rsq_f32_e32 v101, v101
	v_mul_f32_e32 v102, 0x4b800000, v93
	v_fmamk_f32 v100, v100, 0x3a800000, v92
	s_waitcnt lgkmcnt(0)
	v_add_f32_e32 v98, v98, v99
	v_cmp_gt_f32_e64 s[2:3], s14, v93
	v_mul_f32_e32 v99, 0x4b800000, v100
	v_cmp_gt_f32_e64 s[4:5], s14, v100
	v_cndmask_b32_e64 v93, v93, v102, s[2:3]
	v_fmamk_f32 v98, v98, 0x3a800000, v92
	v_rsq_f32_e32 v93, v93
	v_cndmask_b32_e64 v99, v100, v99, s[4:5]
	v_mul_f32_e32 v100, 0x4b800000, v98
	v_cmp_gt_f32_e32 vcc, s14, v98
	v_rsq_f32_e32 v99, v99
	s_nop 0
	v_cndmask_b32_e32 v98, v98, v100, vcc
	v_mul_f32_e32 v100, 0x45800000, v101
	v_rsq_f32_e32 v98, v98
	v_cndmask_b32_e64 v100, v101, v100, s[0:1]
	v_mul_f32_e32 v28, v28, v100
	v_mul_f32_e32 v29, v29, v100
	v_mul_f32_e32 v30, v30, v100
	v_mul_f32_e32 v31, v31, v100
	v_mul_f32_e32 v24, v24, v100
	v_mul_f32_e32 v25, v25, v100
	v_mul_f32_e32 v26, v26, v100
	v_mul_f32_e32 v27, v27, v100
	v_mul_f32_e32 v20, v20, v100
	v_mul_f32_e32 v21, v21, v100
	v_mul_f32_e32 v22, v22, v100
	v_mul_f32_e32 v23, v23, v100
	v_mul_f32_e32 v16, v16, v100
	v_mul_f32_e32 v17, v17, v100
	v_mul_f32_e32 v18, v18, v100
	v_mul_f32_e32 v19, v19, v100
	v_mul_f32_e32 v100, 0x45800000, v93
	v_mul_f32_e32 v28, v12, v28
	v_mul_f32_e32 v29, v13, v29
	v_mul_f32_e32 v24, v8, v24
	v_mul_f32_e32 v25, v9, v25
	v_mul_f32_e32 v26, v10, v26
	v_mul_f32_e32 v20, v4, v20
	v_cndmask_b32_e64 v93, v93, v100, s[2:3]
	v_mul_f32_e32 v100, 0x45800000, v99
	v_mul_f32_e32 v30, v14, v30
	v_mul_f32_e32 v31, v15, v31
	v_mul_f32_e32 v27, v11, v27
	v_mul_f32_e32 v21, v5, v21
	v_mul_f32_e32 v22, v6, v22
	v_mul_f32_e32 v23, v7, v23
	v_mul_f32_e32 v101, v0, v16
	v_mul_f32_e32 v102, v1, v17
	v_mul_f32_e32 v103, v2, v18
	v_mul_f32_e32 v104, v3, v19
	v_cvt_pk_bf16_f32 v16, v28, v29
	v_cvt_pk_bf16_f32 v17, v30, v31
	v_cvt_pk_bf16_f32 v18, v24, v25
	v_cvt_pk_bf16_f32 v19, v26, v27
	v_cvt_pk_bf16_f32 v20, v20, v21
	v_mul_f32_e32 v24, v94, v93
	v_mul_f32_e32 v25, v95, v93
	v_mul_f32_e32 v26, v96, v93
	v_mul_f32_e32 v28, v72, v93
	v_mul_f32_e32 v29, v73, v93
	v_mul_f32_e32 v68, v68, v93
	v_mul_f32_e32 v69, v69, v93
	v_mul_f32_e32 v64, v64, v93
	v_cndmask_b32_e64 v72, v99, v100, s[4:5]
	v_mul_f32_e32 v73, 0x45800000, v98
	v_cvt_pk_bf16_f32 v21, v22, v23
	v_cvt_pk_bf16_f32 v22, v101, v102
	v_cvt_pk_bf16_f32 v23, v103, v104
	v_mul_f32_e32 v27, v97, v93
	v_mul_f32_e32 v30, v74, v93
	v_mul_f32_e32 v31, v75, v93
	v_mul_f32_e32 v70, v70, v93
	v_mul_f32_e32 v71, v71, v93
	global_store_dwordx2 v[80:81], v[16:17], off
	global_store_dwordx2 v[80:81], v[18:19], off offset:512
	global_store_dwordx2 v[80:81], v[20:21], off offset:1024
	global_store_dwordx2 v[80:81], v[22:23], off offset:1536
	v_mul_f32_e32 v16, v12, v24
	v_mul_f32_e32 v17, v13, v25
	v_mul_f32_e32 v18, v14, v26
	v_mul_f32_e32 v20, v8, v28
	v_mul_f32_e32 v24, v4, v68
	v_mul_f32_e32 v25, v5, v69
	v_mul_f32_e32 v28, v0, v64
	v_mul_f32_e32 v60, v60, v72
	v_mul_f32_e32 v61, v61, v72
	v_cndmask_b32_e32 v64, v98, v73, vcc
	v_mul_f32_e32 v65, v65, v93
	v_mul_f32_e32 v66, v66, v93
	v_mul_f32_e32 v67, v67, v93
	v_mul_f32_e32 v19, v15, v27
	v_mul_f32_e32 v21, v9, v29
	v_mul_f32_e32 v22, v10, v30
	v_mul_f32_e32 v23, v11, v31
	v_mul_f32_e32 v26, v6, v70
	v_mul_f32_e32 v27, v7, v71
	v_mul_f32_e32 v62, v62, v72
	v_mul_f32_e32 v63, v63, v72
	v_mul_f32_e32 v52, v52, v72
	v_mul_f32_e32 v53, v53, v72
	v_mul_f32_e32 v54, v54, v72
	v_mul_f32_e32 v55, v55, v72
	v_mul_f32_e32 v48, v48, v72
	v_mul_f32_e32 v49, v49, v72
	v_cvt_pk_bf16_f32 v16, v16, v17
	v_cvt_pk_bf16_f32 v17, v18, v19
	v_cvt_pk_bf16_f32 v18, v20, v21
	v_cvt_pk_bf16_f32 v20, v24, v25
	v_mul_f32_e32 v24, v12, v60
	v_mul_f32_e32 v25, v13, v61
	v_mul_f32_e32 v44, v44, v64
	v_mul_f32_e32 v45, v45, v64
	v_mul_f32_e32 v46, v46, v64
	v_mul_f32_e32 v47, v47, v64
	v_mul_f32_e32 v36, v36, v64
	v_mul_f32_e32 v37, v37, v64
	v_mul_f32_e32 v38, v38, v64
	v_mul_f32_e32 v39, v39, v64
	v_mul_f32_e32 v32, v32, v64
	v_mul_f32_e32 v33, v33, v64
	v_mul_f32_e32 v29, v1, v65
	v_mul_f32_e32 v30, v2, v66
	v_mul_f32_e32 v31, v3, v67
	v_mul_f32_e32 v56, v56, v72
	v_mul_f32_e32 v57, v57, v72
	v_mul_f32_e32 v58, v58, v72
	v_mul_f32_e32 v59, v59, v72
	v_mul_f32_e32 v50, v50, v72
	v_mul_f32_e32 v51, v51, v72
	v_cvt_pk_bf16_f32 v19, v22, v23
	v_cvt_pk_bf16_f32 v21, v26, v27
	v_cvt_pk_bf16_f32 v22, v28, v29
	v_cvt_pk_bf16_f32 v23, v30, v31
	v_mul_f32_e32 v26, v14, v62
	v_mul_f32_e32 v27, v15, v63
	v_mul_f32_e32 v52, v4, v52
	v_mul_f32_e32 v53, v5, v53
	v_mul_f32_e32 v54, v6, v54
	v_mul_f32_e32 v55, v7, v55
	v_mul_f32_e32 v48, v0, v48
	v_mul_f32_e32 v49, v1, v49
	v_mul_f32_e32 v40, v40, v64
	v_mul_f32_e32 v41, v41, v64
	v_mul_f32_e32 v42, v42, v64
	v_mul_f32_e32 v43, v43, v64
	v_mul_f32_e32 v34, v34, v64
	v_mul_f32_e32 v35, v35, v64
	global_store_dwordx2 v[80:81], v[16:17], off offset:2048
	global_store_dwordx2 v[80:81], v[18:19], off offset:2560
	global_store_dwordx2 v[80:81], v[20:21], off offset:3072
	global_store_dwordx2 v[80:81], v[22:23], off offset:3584
	v_cvt_pk_bf16_f32 v16, v24, v25
	v_cvt_pk_bf16_f32 v17, v26, v27
	v_mul_f32_e32 v12, v12, v44
	v_mul_f32_e32 v13, v13, v45
	v_mul_f32_e32 v14, v14, v46
	v_mul_f32_e32 v15, v15, v47
	v_mul_f32_e32 v4, v4, v36
	v_mul_f32_e32 v5, v5, v37
	v_mul_f32_e32 v6, v6, v38
	v_mul_f32_e32 v7, v7, v39
	v_mul_f32_e32 v24, v0, v32
	v_mul_f32_e32 v25, v1, v33
	v_lshl_add_u64 v[80:81], v[80:81], 0, s[10:11]
	v_cvt_pk_bf16_f32 v0, v12, v13
	v_cvt_pk_bf16_f32 v1, v14, v15
	v_mul_f32_e32 v28, v8, v56
	v_mul_f32_e32 v29, v9, v57
	v_mul_f32_e32 v30, v10, v58
	v_mul_f32_e32 v31, v11, v59
	v_mul_f32_e32 v50, v2, v50
	v_mul_f32_e32 v51, v3, v51
	v_cvt_pk_bf16_f32 v18, v28, v29
	v_cvt_pk_bf16_f32 v19, v30, v31
	v_cvt_pk_bf16_f32 v20, v52, v53
	v_cvt_pk_bf16_f32 v21, v54, v55
	v_cvt_pk_bf16_f32 v22, v48, v49
	v_cvt_pk_bf16_f32 v23, v50, v51
	v_mul_f32_e32 v8, v8, v40
	v_mul_f32_e32 v9, v9, v41
	v_mul_f32_e32 v10, v10, v42
	v_mul_f32_e32 v11, v11, v43
	v_mul_f32_e32 v26, v2, v34
	v_mul_f32_e32 v27, v3, v35
	global_store_dwordx2 v[84:85], v[16:17], off
	global_store_dwordx2 v[84:85], v[18:19], off offset:512
	global_store_dwordx2 v[84:85], v[20:21], off offset:1024
	global_store_dwordx2 v[84:85], v[22:23], off offset:1536
	v_cvt_pk_bf16_f32 v2, v8, v9
	v_cvt_pk_bf16_f32 v3, v10, v11
	v_cvt_pk_bf16_f32 v4, v4, v5
	v_cvt_pk_bf16_f32 v5, v6, v7
	v_cvt_pk_bf16_f32 v6, v24, v25
	v_cvt_pk_bf16_f32 v7, v26, v27
	global_store_dwordx2 v[84:85], v[0:1], off offset:2048
	global_store_dwordx2 v[84:85], v[2:3], off offset:2560
	global_store_dwordx2 v[84:85], v[4:5], off offset:3072
	global_store_dwordx2 v[84:85], v[6:7], off offset:3584
	s_cbranch_scc0 .LBB0_1710

.LBB0_1950:
	s_or_b64 exec, exec, s[34:35]
	s_waitcnt lgkmcnt(0)
	s_barrier
	s_and_b64 vcc, exec, s[6:7]
	v_ashrrev_i32_e32 v185, 31, v184
	s_cbranch_vccnz .LBB0_1953
	s_bfe_u32 s98, s72, 0x20002
	s_cmp_eq_u32 s98, 3
	s_cbranch_scc1 .LBB0_1953
	s_movk_i32 s100, 0x2000
	s_movk_i32 s101, 0x4000
	s_cmp_eq_u32 s98, 1
	s_cselect_b32 s100, 8, s100
	s_cselect_b32 s101, 0x1ff8, s101
	s_cmp_eq_u32 s98, 2
	s_cselect_b32 s101, 4, s101
	s_cmp_eq_u32 s98, 0
	s_cselect_b32 s98, 2, 3
	s_mov_b32 s99, 0
	v_and_b32_e32 v0, 64, v198
	v_add_u32_e32 v0, 64, v0
	v_xor_b32_e32 v1, 1, v198
	v_cmp_lt_i32_e32 vcc, v1, v0
	s_ashr_i32 s73, s72, 31
	s_lshl_b32 s6, s94, 5
	v_cndmask_b32_e32 v1, v198, v1, vcc
	v_lshlrev_b32_e32 v44, 2, v1
	v_xor_b32_e32 v1, 2, v198
	v_cmp_lt_i32_e32 vcc, v1, v0
	s_lshl_b64 s[0:1], s[72:73], 12
	s_add_u32 s0, s52, s0
	v_cndmask_b32_e32 v1, v198, v1, vcc
	v_lshlrev_b32_e32 v45, 2, v1
	v_xor_b32_e32 v1, 4, v198
	v_cmp_lt_i32_e32 vcc, v1, v0
	s_addc_u32 s1, s53, s1
	s_ashr_i32 s7, s6, 31
	v_cndmask_b32_e32 v1, v198, v1, vcc
	v_lshlrev_b32_e32 v46, 2, v1
	v_xor_b32_e32 v1, 8, v198
	v_cmp_lt_i32_e32 vcc, v1, v0
	s_lshl_b64 s[8:9], s[6:7], 12
	s_mov_b32 s10, 0x3a800000
	v_cndmask_b32_e32 v1, v198, v1, vcc
	v_lshlrev_b32_e32 v47, 2, v1
	v_xor_b32_e32 v1, 16, v198
	v_cmp_lt_i32_e32 vcc, v1, v0
	s_mov_b32 s7, 0x800000
	s_nop 0
	v_cndmask_b32_e32 v1, v198, v1, vcc
	v_lshlrev_b32_e32 v48, 2, v1
	v_xor_b32_e32 v1, 32, v198
	v_cmp_lt_i32_e32 vcc, v1, v0
	s_nop 1
	v_cndmask_b32_e32 v0, v198, v1, vcc
	v_lshlrev_b32_e32 v49, 2, v0
	v_lshlrev_b64 v[0:1], 4, v[184:185]
	v_lshl_add_u64 v[34:35], s[0:1], 0, v[0:1]
	s_mov_b32 s0, 0x358637bd
	v_lshl_add_u64 v[32:33], s[50:51], 0, v[0:1]
	v_mov_b64_e32 v[36:37], s[0:1]
.LBB0_1952:
	v_add_co_u32_e32 v38, vcc, 0x1000, v34
	global_load_dwordx4 v[24:27], v[34:35], off
	global_load_dwordx4 v[20:23], v[34:35], off offset:1024
	global_load_dwordx4 v[16:19], v[34:35], off offset:3072
	global_load_dwordx4 v[28:31], v[34:35], off offset:2048
	v_addc_co_u32_e32 v39, vcc, 0, v35, vcc
	v_add_co_u32_e32 v40, vcc, 0x2000, v34
	global_load_dwordx4 v[12:15], v[32:33], off
	global_load_dwordx4 v[8:11], v[32:33], off offset:1024
	global_load_dwordx4 v[4:7], v[32:33], off offset:2048
	global_load_dwordx4 v[0:3], v[32:33], off offset:3072
	global_load_dwordx4 v[50:53], v[38:39], off
	global_load_dwordx4 v[54:57], v[38:39], off offset:1024
	global_load_dwordx4 v[58:61], v[38:39], off offset:3072
	global_load_dwordx4 v[62:65], v[38:39], off offset:2048
	v_addc_co_u32_e32 v41, vcc, 0, v35, vcc
	global_load_dwordx4 v[66:69], v[40:41], off
	global_load_dwordx4 v[70:73], v[40:41], off offset:1024
	global_load_dwordx4 v[74:77], v[40:41], off offset:3072
	global_load_dwordx4 v[78:81], v[40:41], off offset:2048
	v_add_co_u32_e32 v42, vcc, 0x3000, v34
	s_add_i32 s99, s99, 1
	s_cmp_eq_u32 s99, 2
	s_cselect_b32 s6, s101, s100
	s_cmp_ge_u32 s99, s98
	s_cselect_b32 s6, 0x4000, s6
	s_lshl_b32 s8, s6, 12
	s_mov_b32 s9, 0
	s_add_i32 s72, s72, s6
	s_nop 0
	v_addc_co_u32_e32 v43, vcc, 0, v35, vcc
	global_load_dwordx4 v[82:85], v[42:43], off
	global_load_dwordx4 v[86:89], v[42:43], off offset:1024
	global_load_dwordx4 v[90:93], v[42:43], off offset:3072
	global_load_dwordx4 v[94:97], v[42:43], off offset:2048
	s_cmpk_gt_i32 s72, 0x3fff
	s_waitcnt vmcnt(0)
	v_pk_mul_f32 v[98:99], v[26:27], v[26:27]
	v_pk_mul_f32 v[100:101], v[24:25], v[24:25]
	v_pk_mul_f32 v[102:103], v[22:23], v[22:23]
	v_pk_mul_f32 v[104:105], v[20:21], v[20:21]
	v_mul_f32_e32 v109, v18, v18
	v_mul_f32_e32 v106, v29, v29
	v_mul_f32_e32 v108, v31, v31
	v_mul_f32_e32 v112, v19, v19
	v_pk_mov_b32 v[110:111], v[100:101], v[98:99] op_sel:[1,0]
	v_mov_b32_e32 v101, v99
	v_pk_mov_b32 v[98:99], v[104:105], v[102:103] op_sel:[1,0]
	v_mov_b32_e32 v105, v103
	v_pk_fma_f32 v[102:103], v[28:29], v[28:29], v[106:107] op_sel_hi:[1,1,0]
	v_pk_fma_f32 v[106:107], v[30:31], v[30:31], v[108:109] op_sel_hi:[1,1,0]
	v_pk_add_f32 v[100:101], v[110:111], v[100:101]
	v_pk_add_f32 v[98:99], v[98:99], v[104:105]
	v_mov_b32_e32 v103, v109
	v_mov_b32_e32 v107, v112
	v_pk_mul_f32 v[104:105], v[52:53], v[52:53]
	v_pk_mul_f32 v[108:109], v[50:51], v[50:51]
	v_pk_mul_f32 v[110:111], v[56:57], v[56:57]
	v_pk_mul_f32 v[112:113], v[54:55], v[54:55]
	v_mul_f32_e32 v114, v63, v63
	v_mul_f32_e32 v116, v65, v65
	v_mul_f32_e32 v125, v16, v16
	v_mul_f32_e32 v127, v17, v17
	v_mul_f32_e32 v128, v60, v60
	v_mul_f32_e32 v129, v61, v61
	v_pk_add_f32 v[100:101], v[100:101], v[100:101] op_sel:[0,1] op_sel_hi:[1,0]
	v_pk_add_f32 v[98:99], v[98:99], v[98:99] op_sel:[0,1] op_sel_hi:[1,0]
	v_pk_add_f32 v[102:103], v[102:103], v[106:107]
	v_pk_mov_b32 v[106:107], v[108:109], v[104:105] op_sel:[1,0]
	v_mov_b32_e32 v109, v105
	v_pk_mov_b32 v[104:105], v[112:113], v[110:111] op_sel:[1,0]
	v_mov_b32_e32 v113, v111
	v_pk_fma_f32 v[110:111], v[62:63], v[62:63], v[114:115] op_sel_hi:[1,1,0]
	v_pk_fma_f32 v[114:115], v[64:65], v[64:65], v[116:117] op_sel_hi:[1,1,0]
	v_pk_mul_f32 v[116:117], v[68:69], v[68:69]
	v_pk_mul_f32 v[118:119], v[66:67], v[66:67]
	v_pk_mul_f32 v[120:121], v[72:73], v[72:73]
	v_pk_mul_f32 v[122:123], v[70:71], v[70:71]
	v_mul_f32_e32 v124, v79, v79
	v_mul_f32_e32 v126, v81, v81
	v_mov_b32_e32 v101, v125
	v_mov_b32_e32 v99, v127
	v_pk_add_f32 v[106:107], v[106:107], v[108:109]
	v_pk_add_f32 v[104:105], v[104:105], v[112:113]
	v_mov_b32_e32 v111, v128
	v_mov_b32_e32 v115, v129
	v_pk_mov_b32 v[108:109], v[118:119], v[116:117] op_sel:[1,0]
	v_mov_b32_e32 v119, v117
	v_pk_mov_b32 v[112:113], v[122:123], v[120:121] op_sel:[1,0]
	v_mov_b32_e32 v123, v121
	v_pk_fma_f32 v[116:117], v[78:79], v[78:79], v[124:125] op_sel_hi:[1,1,0]
	v_pk_fma_f32 v[120:121], v[80:81], v[80:81], v[126:127] op_sel_hi:[1,1,0]
	v_pk_mul_f32 v[124:125], v[84:85], v[84:85]
	v_pk_mul_f32 v[126:127], v[82:83], v[82:83]
	v_pk_mul_f32 v[128:129], v[88:89], v[88:89]
	v_pk_mul_f32 v[130:131], v[86:87], v[86:87]
	v_mul_f32_e32 v133, v58, v58
	v_mul_f32_e32 v135, v59, v59
	v_pk_add_f32 v[98:99], v[100:101], v[98:99]
	v_pk_add_f32 v[100:101], v[106:107], v[106:107] op_sel:[0,1] op_sel_hi:[1,0]
	v_pk_add_f32 v[104:105], v[104:105], v[104:105] op_sel:[0,1] op_sel_hi:[1,0]
	v_pk_add_f32 v[106:107], v[110:111], v[114:115]
	v_pk_add_f32 v[108:109], v[108:109], v[118:119]
	v_pk_add_f32 v[110:111], v[112:113], v[122:123]
	v_pk_mov_b32 v[112:113], v[126:127], v[124:125] op_sel:[1,0]
	v_mov_b32_e32 v127, v125
	v_pk_mov_b32 v[114:115], v[130:131], v[128:129] op_sel:[1,0]
	v_mov_b32_e32 v131, v129
	v_mul_f32_e32 v136, v74, v74
	v_mul_f32_e32 v137, v75, v75
	v_mul_f32_e32 v138, v76, v76
	v_mul_f32_e32 v139, v77, v77
	v_mul_f32_e32 v132, v95, v95
	v_mul_f32_e32 v134, v97, v97
	v_pk_add_f32 v[98:99], v[98:99], v[102:103]
	v_mov_b32_e32 v101, v133
	v_mov_b32_e32 v105, v135
	v_pk_add_f32 v[102:103], v[108:109], v[108:109] op_sel:[0,1] op_sel_hi:[1,0]
	v_pk_add_f32 v[108:109], v[110:111], v[110:111] op_sel:[0,1] op_sel_hi:[1,0]
	v_pk_add_f32 v[112:113], v[112:113], v[126:127]
	v_pk_add_f32 v[114:115], v[114:115], v[130:131]
	v_mul_f32_e32 v140, v90, v90
	v_mul_f32_e32 v141, v91, v91
	v_mul_f32_e32 v142, v92, v92
	v_mul_f32_e32 v143, v93, v93
	v_mov_b32_e32 v117, v138
	v_mov_b32_e32 v121, v139
	v_pk_fma_f32 v[118:119], v[94:95], v[94:95], v[132:133] op_sel_hi:[1,1,0]
	v_pk_fma_f32 v[122:123], v[96:97], v[96:97], v[134:135] op_sel_hi:[1,1,0]
	v_pk_add_f32 v[100:101], v[100:101], v[104:105]
	v_mov_b32_e32 v103, v136
	v_mov_b32_e32 v109, v137
	v_pk_add_f32 v[112:113], v[112:113], v[112:113] op_sel:[0,1] op_sel_hi:[1,0]
	v_pk_add_f32 v[114:115], v[114:115], v[114:115] op_sel:[0,1] op_sel_hi:[1,0]
	v_pk_add_f32 v[110:111], v[116:117], v[120:121]
	v_mov_b32_e32 v119, v142
	v_mov_b32_e32 v123, v143
	v_pk_add_f32 v[100:101], v[100:101], v[106:107]
	v_pk_add_f32 v[102:103], v[102:103], v[108:109]
	v_mov_b32_e32 v113, v140
	v_mov_b32_e32 v115, v141
	v_mov_b32_e32 v105, v98
	v_pk_add_f32 v[116:117], v[118:119], v[122:123]
	v_mov_b32_e32 v104, v100
	v_mov_b32_e32 v98, v101
	v_pk_add_f32 v[100:101], v[102:103], v[110:111]
	v_pk_add_f32 v[102:103], v[112:113], v[114:115]
	v_pk_add_f32 v[98:99], v[104:105], v[98:99]
	v_pk_add_f32 v[102:103], v[102:103], v[116:117]
	v_mov_b32_e32 v105, v100
	ds_bpermute_b32 v107, v44, v99
	ds_bpermute_b32 v106, v44, v98
	v_mov_b32_e32 v104, v102
	v_mov_b32_e32 v100, v103
	v_pk_add_f32 v[100:101], v[104:105], v[100:101]
	ds_bpermute_b32 v103, v44, v101
	ds_bpermute_b32 v102, v44, v100
	s_waitcnt lgkmcnt(2)
	v_pk_add_f32 v[98:99], v[98:99], v[106:107]
	ds_bpermute_b32 v105, v45, v99
	ds_bpermute_b32 v104, v45, v98
	s_waitcnt lgkmcnt(2)
	v_pk_add_f32 v[100:101], v[100:101], v[102:103]
	ds_bpermute_b32 v103, v45, v101
	ds_bpermute_b32 v102, v45, v100
	s_waitcnt lgkmcnt(2)
	v_pk_add_f32 v[98:99], v[98:99], v[104:105]
	ds_bpermute_b32 v105, v46, v99
	ds_bpermute_b32 v104, v46, v98
	s_waitcnt lgkmcnt(2)
	v_pk_add_f32 v[100:101], v[100:101], v[102:103]
	ds_bpermute_b32 v103, v46, v101
	ds_bpermute_b32 v102, v46, v100
	s_waitcnt lgkmcnt(2)
	v_pk_add_f32 v[98:99], v[98:99], v[104:105]
	ds_bpermute_b32 v105, v47, v99
	ds_bpermute_b32 v104, v47, v98
	s_waitcnt lgkmcnt(2)
	v_pk_add_f32 v[100:101], v[100:101], v[102:103]
	ds_bpermute_b32 v103, v47, v101
	ds_bpermute_b32 v102, v47, v100
	s_waitcnt lgkmcnt(2)
	v_pk_add_f32 v[98:99], v[98:99], v[104:105]
	ds_bpermute_b32 v105, v48, v99
	ds_bpermute_b32 v104, v48, v98
	s_waitcnt lgkmcnt(2)
	v_pk_add_f32 v[100:101], v[100:101], v[102:103]
	ds_bpermute_b32 v103, v48, v101
	ds_bpermute_b32 v102, v48, v100
	s_waitcnt lgkmcnt(2)
	v_pk_add_f32 v[98:99], v[98:99], v[104:105]
	ds_bpermute_b32 v105, v49, v99
	ds_bpermute_b32 v104, v49, v98
	s_waitcnt lgkmcnt(2)
	v_pk_add_f32 v[100:101], v[100:101], v[102:103]
	ds_bpermute_b32 v103, v49, v101
	ds_bpermute_b32 v102, v49, v100
	s_waitcnt lgkmcnt(2)
	v_pk_add_f32 v[98:99], v[98:99], v[104:105]
	s_waitcnt lgkmcnt(0)
	v_pk_add_f32 v[100:101], v[100:101], v[102:103]
	v_pk_fma_f32 v[98:99], v[98:99], s[10:11], v[36:37] op_sel_hi:[1,0,0]
	s_nop 0
	v_mul_f32_e32 v104, 0x4b800000, v99
	v_mul_f32_e32 v105, 0x4b800000, v98
	v_cmp_gt_f32_e32 vcc, s7, v98
	v_cmp_gt_f32_e64 s[0:1], s7, v99
	s_nop 0
	v_cndmask_b32_e32 v103, v98, v105, vcc
	v_cndmask_b32_e64 v102, v99, v104, s[0:1]
	v_pk_fma_f32 v[98:99], v[100:101], s[10:11], v[36:37] op_sel_hi:[1,0,0]
	v_rsq_f32_e32 v100, v102
	v_mul_f32_e32 v102, 0x4b800000, v99
	v_cmp_gt_f32_e64 s[4:5], s7, v99
	v_rsq_f32_e32 v101, v103
	v_mul_f32_e32 v103, 0x4b800000, v98
	v_cmp_gt_f32_e64 s[2:3], s7, v98
	v_cndmask_b32_e64 v99, v99, v102, s[4:5]
	v_rsq_f32_e32 v106, v99
	v_cndmask_b32_e64 v98, v98, v103, s[2:3]
	v_rsq_f32_e32 v107, v98
	v_mul_f32_e32 v98, 0x45800000, v100
	v_mul_f32_e32 v99, 0x45800000, v101
	v_cndmask_b32_e64 v98, v100, v98, s[0:1]
	v_cndmask_b32_e32 v100, v101, v99, vcc
	v_pk_mul_f32 v[24:25], v[98:99], v[24:25] op_sel_hi:[0,1]
	v_pk_mul_f32 v[26:27], v[98:99], v[26:27] op_sel_hi:[0,1]
	v_pk_mul_f32 v[20:21], v[98:99], v[20:21] op_sel_hi:[0,1]
	v_pk_mul_f32 v[22:23], v[98:99], v[22:23] op_sel_hi:[0,1]
	v_pk_mul_f32 v[28:29], v[98:99], v[28:29] op_sel_hi:[0,1]
	v_pk_mul_f32 v[30:31], v[98:99], v[30:31] op_sel_hi:[0,1]
	v_pk_mul_f32 v[102:103], v[98:99], v[16:17] op_sel_hi:[0,1]
	v_pk_mul_f32 v[98:99], v[98:99], v[18:19] op_sel_hi:[0,1]
	v_mul_f32_e32 v108, 0x45800000, v106
	v_pk_mul_f32 v[50:51], v[100:101], v[50:51] op_sel_hi:[0,1]
	v_pk_mul_f32 v[52:53], v[100:101], v[52:53] op_sel_hi:[0,1]
	v_pk_mul_f32 v[54:55], v[100:101], v[54:55] op_sel_hi:[0,1]
	v_pk_mul_f32 v[56:57], v[100:101], v[56:57] op_sel_hi:[0,1]
	v_pk_mul_f32 v[62:63], v[100:101], v[62:63] op_sel_hi:[0,1]
	v_pk_mul_f32 v[64:65], v[100:101], v[64:65] op_sel_hi:[0,1]
	v_pk_mul_f32 v[104:105], v[100:101], v[58:59] op_sel_hi:[0,1]
	v_pk_mul_f32 v[100:101], v[100:101], v[60:61] op_sel_hi:[0,1]
	v_mul_f32_e32 v109, 0x45800000, v107
	v_pk_mul_f32 v[18:19], v[26:27], v[14:15]
	v_pk_mul_f32 v[16:17], v[24:25], v[12:13]
	v_pk_mul_f32 v[26:27], v[30:31], v[6:7]
	v_pk_mul_f32 v[30:31], v[98:99], v[2:3]
	v_cndmask_b32_e64 v98, v106, v108, s[4:5]
	v_pk_mul_f32 v[22:23], v[22:23], v[10:11]
	v_pk_mul_f32 v[20:21], v[20:21], v[8:9]
	v_pk_mul_f32 v[24:25], v[28:29], v[4:5]
	v_pk_mul_f32 v[28:29], v[102:103], v[0:1]
	v_pk_mul_f32 v[52:53], v[52:53], v[14:15]
	v_pk_mul_f32 v[50:51], v[50:51], v[12:13]
	v_pk_mul_f32 v[56:57], v[56:57], v[10:11]
	v_pk_mul_f32 v[54:55], v[54:55], v[8:9]
	v_pk_mul_f32 v[60:61], v[64:65], v[6:7]
	v_pk_mul_f32 v[58:59], v[62:63], v[4:5]
	v_pk_mul_f32 v[64:65], v[100:101], v[2:3]
	v_pk_mul_f32 v[62:63], v[104:105], v[0:1]
	v_cndmask_b32_e64 v100, v107, v109, s[2:3]
	global_store_dwordx4 v[34:35], v[16:19], off
	global_store_dwordx4 v[34:35], v[20:23], off offset:1024
	global_store_dwordx4 v[34:35], v[24:27], off offset:2048
	global_store_dwordx4 v[34:35], v[28:31], off offset:3072
	global_store_dwordx4 v[38:39], v[50:53], off
	global_store_dwordx4 v[38:39], v[54:57], off offset:1024
	global_store_dwordx4 v[38:39], v[58:61], off offset:2048
	global_store_dwordx4 v[38:39], v[62:65], off offset:3072
	v_pk_mul_f32 v[16:17], v[98:99], v[66:67] op_sel_hi:[0,1]
	v_pk_mul_f32 v[18:19], v[98:99], v[68:69] op_sel_hi:[0,1]
	v_pk_mul_f32 v[20:21], v[98:99], v[70:71] op_sel_hi:[0,1]
	v_pk_mul_f32 v[22:23], v[98:99], v[72:73] op_sel_hi:[0,1]
	v_pk_mul_f32 v[24:25], v[98:99], v[78:79] op_sel_hi:[0,1]
	v_pk_mul_f32 v[26:27], v[98:99], v[80:81] op_sel_hi:[0,1]
	v_pk_mul_f32 v[28:29], v[98:99], v[74:75] op_sel_hi:[0,1]
	v_pk_mul_f32 v[30:31], v[98:99], v[76:77] op_sel_hi:[0,1]
	v_pk_mul_f32 v[38:39], v[100:101], v[82:83] op_sel_hi:[0,1]
	v_pk_mul_f32 v[50:51], v[100:101], v[84:85] op_sel_hi:[0,1]
	v_pk_mul_f32 v[52:53], v[100:101], v[86:87] op_sel_hi:[0,1]
	v_pk_mul_f32 v[54:55], v[100:101], v[88:89] op_sel_hi:[0,1]
	v_pk_mul_f32 v[56:57], v[100:101], v[94:95] op_sel_hi:[0,1]
	v_pk_mul_f32 v[58:59], v[100:101], v[96:97] op_sel_hi:[0,1]
	v_pk_mul_f32 v[60:61], v[100:101], v[90:91] op_sel_hi:[0,1]
	v_pk_mul_f32 v[62:63], v[100:101], v[92:93] op_sel_hi:[0,1]
	v_lshl_add_u64 v[34:35], v[34:35], 0, s[8:9]
	v_pk_mul_f32 v[18:19], v[18:19], v[14:15]
	v_pk_mul_f32 v[16:17], v[16:17], v[12:13]
	v_pk_mul_f32 v[22:23], v[22:23], v[10:11]
	v_pk_mul_f32 v[20:21], v[20:21], v[8:9]
	v_pk_mul_f32 v[26:27], v[26:27], v[6:7]
	v_pk_mul_f32 v[24:25], v[24:25], v[4:5]
	v_pk_mul_f32 v[30:31], v[30:31], v[2:3]
	v_pk_mul_f32 v[28:29], v[28:29], v[0:1]
	v_pk_mul_f32 v[14:15], v[50:51], v[14:15]
	v_pk_mul_f32 v[12:13], v[38:39], v[12:13]
	v_pk_mul_f32 v[10:11], v[54:55], v[10:11]
	v_pk_mul_f32 v[8:9], v[52:53], v[8:9]
	v_pk_mul_f32 v[6:7], v[58:59], v[6:7]
	v_pk_mul_f32 v[4:5], v[56:57], v[4:5]
	v_pk_mul_f32 v[2:3], v[62:63], v[2:3]
	v_pk_mul_f32 v[0:1], v[60:61], v[0:1]
	global_store_dwordx4 v[40:41], v[16:19], off
	global_store_dwordx4 v[40:41], v[20:23], off offset:1024
	global_store_dwordx4 v[40:41], v[24:27], off offset:2048
	global_store_dwordx4 v[40:41], v[28:31], off offset:3072
	global_store_dwordx4 v[42:43], v[12:15], off
	global_store_dwordx4 v[42:43], v[8:11], off offset:1024
	global_store_dwordx4 v[42:43], v[4:7], off offset:2048
	global_store_dwordx4 v[42:43], v[0:3], off offset:3072
	s_cbranch_scc0 .LBB0_1952
